# attention loop: K/V prefetch kept in flight across the LDS-store wait (global loads + counted vmcnt)
# speedup vs baseline: 1.0245x; 1.0023x over previous
; #define SBAR() __builtin_amdgcn_sched_barrier(0)
; DI void finishSM(f32x16& p0, f32x16& p1, float alpha, float& l_reg, bf16x8& pa0, bf16x8& pa1, bf16x8& pa2, bf16x8& pa3) {
; #pragma unroll
;   for (int r = 0; r < 16; ++r) p1[r] = __builtin_amdgcn_exp2f(p1[r]);
;   float ps = 0;
; #pragma unroll
;   for (int r = 0; r < 16; ++r) ps += p0[r];
; #pragma unroll
;   for (int r = 0; r < 16; ++r) ps += p1[r];
;   { auto rr = __builtin_amdgcn_permlane32_swap(__float_as_uint(ps), __float_as_uint(ps), false, false);
;     ps = __uint_as_float(rr[0]) + __uint_as_float(rr[1]); }
;   l_reg = l_reg * alpha + ps;
;     ...
;   PK4(p0, 0, pa0); PK4(p0, 8, pa1); PK4(p1, 0, pa2); PK4(p1, 8, pa3);
;     ...
; }
; DI void qkt(f32x16& p0, f32x16& p1, const char* Ks, const bf16x8* qr, int r32, int hi) {
;   p0 = f32x16{}; p1 = f32x16{};
; #pragma unroll
;   for (int d0 = 0; d0 < 6; ++d0) { const int cb = (d0 * 16 + hi * 8) * 2;
;     bf16x8 b0 = *reinterpret_cast<const bf16x8*>(Ks + KSWZ(r32, cb));
;     bf16x8 b1 = *reinterpret_cast<const bf16x8*>(Ks + KSWZ(32 + r32, cb));
;     p0 = __builtin_amdgcn_mfma_f32_32x32x16_bf16(b0, qr[d0], p0, 0, 0, 0);
;     p1 = __builtin_amdgcn_mfma_f32_32x32x16_bf16(b1, qr[d0], p1, 0, 0, 0); }
; }
; template <int D0> DI void pv_one(f32x16& od, int vb, bf16x8 pa0, bf16x8 pa1, bf16x8 pa2, bf16x8 pa3) {
;   const s16x4 l0 = tr_read<v_rd_off(D0, 0, 0)>(vb), h0 = tr_read<v_rd_off(D0, 0, 1)>(vb), l1 = tr_read<v_rd_off(D0, 1, 0)>(vb), h1 = tr_read<v_rd_off(D0, 1, 1)>(vb);
;   const s16x4 l2 = tr_read<v_rd_off(D0, 2, 0)>(vb), h2 = tr_read<v_rd_off(D0, 2, 1)>(vb), l3 = tr_read<v_rd_off(D0, 3, 0)>(vb), h3 = tr_read<v_rd_off(D0, 3, 1)>(vb);
;   asm volatile("s_waitcnt lgkmcnt(0)" ::: "memory"); SBAR();
;     ...
;   od = __builtin_amdgcn_mfma_f32_32x32x16_bf16(pa0, PK(l0, h0), od, 0, 0, 0);
;   od = __builtin_amdgcn_mfma_f32_32x32x16_bf16(pa1, PK(l1, h1), od, 0, 0, 0);
;   od = __builtin_amdgcn_mfma_f32_32x32x16_bf16(pa2, PK(l2, h2), od, 0, 0, 0);
;   od = __builtin_amdgcn_mfma_f32_32x32x16_bf16(pa3, PK(l3, h3), od, 0, 0, 0);
;     ...
; }
.LBB0_2501:
	ds_read_b128 v[34:37], v167 offset:32768
	ds_read_b128 v[38:41], v167 offset:40960
	ds_read_b128 v[102:105], v169 offset:32768
	ds_read_b128 v[200:203], v169 offset:40960
	v_exp_f32_e32 v123, v114
	v_add_f32_e32 v114, 0, v158
	s_waitcnt lgkmcnt(3)
	v_mfma_f32_32x32x16_bf16 v[50:65], v[34:37], v[86:89], 0
	v_add_f32_e32 v114, v195, v114
	v_add_f32_e32 v114, v159, v114
	v_add_f32_e32 v114, v196, v114
	v_add_f32_e32 v114, v193, v114
	v_add_f32_e32 v114, v197, v114
	v_add_f32_e32 v114, v194, v114
	v_add_f32_e32 v114, v198, v114
	s_waitcnt lgkmcnt(2)
	v_mfma_f32_32x32x16_bf16 v[34:49], v[38:41], v[86:89], 0
	v_add_f32_e32 v114, v126, v114
	v_add_f32_e32 v114, v140, v114
	v_add_f32_e32 v114, v127, v114
	v_add_f32_e32 v114, v141, v114
	v_add_f32_e32 v114, v128, v114
	v_add_f32_e32 v114, v156, v114
	v_add_f32_e32 v114, v129, v114
	s_waitcnt lgkmcnt(1)
	v_mfma_f32_32x32x16_bf16 v[50:65], v[102:105], v[82:85], v[50:65]
	v_add_f32_e32 v114, v157, v114
	v_exp_f32_e32 v152, v115
	v_exp_f32_e32 v110, v110
	v_exp_f32_e32 v111, v111
	v_exp_f32_e32 v108, v108
	v_exp_f32_e32 v109, v109
	v_exp_f32_e32 v153, v120
	s_waitcnt lgkmcnt(0)
	v_mfma_f32_32x32x16_bf16 v[34:49], v[200:203], v[82:85], v[34:49]
	ds_read_b128 v[102:105], v168 offset:32768
	ds_read_b128 v[200:203], v168 offset:40960
	v_exp_f32_e32 v199, v121
	v_exp_f32_e32 v112, v112
	v_exp_f32_e32 v113, v113
	v_exp_f32_e32 v106, v106
	v_exp_f32_e32 v107, v107
	s_waitcnt lgkmcnt(1)
	v_mfma_f32_32x32x16_bf16 v[50:65], v[102:105], v[78:81], v[50:65]
	s_waitcnt lgkmcnt(0)
	v_mfma_f32_32x32x16_bf16 v[34:49], v[200:203], v[78:81], v[34:49]
	ds_read_b128 v[102:105], v170 offset:32768
	ds_read_b128 v[200:203], v170 offset:40960
	s_waitcnt lgkmcnt(1)
	v_mfma_f32_32x32x16_bf16 v[50:65], v[102:105], v[74:77], v[50:65]
	s_waitcnt lgkmcnt(0)
	v_mfma_f32_32x32x16_bf16 v[34:49], v[200:203], v[74:77], v[34:49]
	ds_read_b128 v[102:105], v188 offset:32768
	ds_read_b128 v[200:203], v188 offset:40960
	s_waitcnt lgkmcnt(1)
	v_mfma_f32_32x32x16_bf16 v[50:65], v[102:105], v[70:73], v[50:65]
	s_waitcnt lgkmcnt(0)
	v_mfma_f32_32x32x16_bf16 v[34:49], v[200:203], v[70:73], v[34:49]
	ds_read_b128 v[102:105], v171 offset:32768
	ds_read_b128 v[200:203], v171 offset:40960
	s_waitcnt lgkmcnt(1)
	v_mfma_f32_32x32x16_bf16 v[50:65], v[102:105], v[66:69], v[50:65]
	v_exp_f32_e32 v102, v118
	v_exp_f32_e32 v103, v119
	v_exp_f32_e32 v104, v116
	v_exp_f32_e32 v105, v117
	v_add_f32_e32 v114, v102, v114
	v_add_f32_e32 v114, v103, v114
	v_add_f32_e32 v114, v104, v114
	v_add_f32_e32 v114, v105, v114
	v_add_f32_e32 v114, v123, v114
	v_add_f32_e32 v114, v152, v114
	v_add_f32_e32 v114, v110, v114
	v_add_f32_e32 v114, v111, v114
	v_add_f32_e32 v114, v108, v114
	v_add_f32_e32 v114, v109, v114
	s_waitcnt lgkmcnt(0)
	v_mfma_f32_32x32x16_bf16 v[34:49], v[200:203], v[66:69], v[34:49]
	v_add_f32_e32 v114, v153, v114
	v_add_f32_e32 v114, v199, v114
	v_add_f32_e32 v114, v112, v114
	v_add_f32_e32 v114, v113, v114
	v_add_f32_e32 v114, v106, v114
	v_add_f32_e32 v190, v107, v114
	v_mov_b32_e32 v191, v190
	v_cvt_pk_bf16_f32 v114, v158, v195
	v_cvt_pk_bf16_f32 v115, v159, v196
	v_cvt_pk_bf16_f32 v116, v193, v197
	v_cvt_pk_bf16_f32 v117, v194, v198
	v_cvt_pk_bf16_f32 v118, v126, v140
	v_cvt_pk_bf16_f32 v119, v127, v141
	v_cvt_pk_bf16_f32 v120, v128, v156
	v_cvt_pk_bf16_f32 v121, v129, v157
	v_cvt_pk_bf16_f32 v124, v102, v103
	v_cvt_pk_bf16_f32 v125, v104, v105
	v_cvt_pk_bf16_f32 v126, v123, v152
	v_cvt_pk_bf16_f32 v127, v110, v111
	v_cvt_pk_bf16_f32 v192, v108, v109
	v_cvt_pk_bf16_f32 v193, v153, v199
	v_cvt_pk_bf16_f32 v194, v112, v113
	s_nop 1
	v_permlane32_swap_b32_e32 v190, v191
	v_permlane32_swap_b32_e32 v114, v116
	v_cvt_pk_bf16_f32 v195, v106, v107
	v_permlane32_swap_b32_e32 v192, v194
	v_permlane32_swap_b32_e32 v115, v117
	v_permlane32_swap_b32_e32 v118, v120
	v_permlane32_swap_b32_e32 v119, v121
	v_permlane32_swap_b32_e32 v124, v126
	v_permlane32_swap_b32_e32 v125, v127
	v_permlane32_swap_b32_e32 v193, v195
	v_lshl_add_u64 v[158:159], s[22:23], 0, v[138:139]
	s_mov_b32 s8, 0x18530000
	v_add_co_u32_e32 v102, vcc, s8, v158
	v_lshl_add_u64 v[156:157], s[22:23], 0, v[136:137]
	s_nop 0
	v_addc_co_u32_e32 v103, vcc, 0, v159, vcc
	v_add_co_u32_e32 v106, vcc, s10, v156
	v_lshl_add_u64 v[140:141], s[22:23], 0, v[134:135]
	s_nop 0
	v_addc_co_u32_e32 v107, vcc, 0, v157, vcc
	v_add_co_u32_e32 v110, vcc, s10, v140
	global_load_dwordx4 v[102:105], v[102:103], off
	s_nop 0
	global_load_dwordx4 v[106:109], v[106:107], off
	v_addc_co_u32_e32 v111, vcc, 0, v141, vcc
	global_load_dwordx4 v[110:113], v[110:111], off
	ds_read_b64_tr_b16 v[196:197], v133 offset:0
	ds_read_b64_tr_b16 v[198:199], v133 offset:0x400
	ds_read_b64_tr_b16 v[200:201], v133 offset:0x800
	ds_read_b64_tr_b16 v[202:203], v133 offset:0xc00
	ds_read_b64_tr_b16 v[204:205], v133 offset:0x1000
	ds_read_b64_tr_b16 v[206:207], v133 offset:0x1400
	ds_read_b64_tr_b16 v[208:209], v133 offset:0x1800
	ds_read_b64_tr_b16 v[210:211], v133 offset:0x1c00
	s_waitcnt lgkmcnt(0)
	s_nop 0
	v_mfma_f32_32x32x16_bf16 v[2:17], v[114:117], v[196:199], v[2:17]
	ds_read_b64_tr_b16 v[196:197], v133 offset:0x200
	ds_read_b64_tr_b16 v[198:199], v133 offset:0x600
	v_mfma_f32_32x32x16_bf16 v[2:17], v[118:121], v[200:203], v[2:17]
	ds_read_b64_tr_b16 v[200:201], v133 offset:0xa00
	ds_read_b64_tr_b16 v[202:203], v133 offset:0xe00
	v_mfma_f32_32x32x16_bf16 v[2:17], v[124:127], v[204:207], v[2:17]
	ds_read_b64_tr_b16 v[204:205], v133 offset:0x1200
	ds_read_b64_tr_b16 v[206:207], v133 offset:0x1600
	v_mfma_f32_32x32x16_bf16 v[2:17], v[192:195], v[208:211], v[2:17]
	ds_read_b64_tr_b16 v[208:209], v133 offset:0x1a00
	ds_read_b64_tr_b16 v[210:211], v133 offset:0x1e00
	s_waitcnt lgkmcnt(0)
; DI void partialSM(f32x16& p0, f32x16& p1, float& m_reg, float& mn, float& alpha) {
;   constexpr float C = SCALE * 1.4426950408889634f;
;   float pmax = p0[0];
; #pragma unroll
;   for (int r = 1; r < 16; ++r) pmax = fmaxf(pmax, p0[r]);
; #pragma unroll
;   for (int r = 0; r < 16; ++r) pmax = fmaxf(pmax, p1[r]);
;   { auto rr = __builtin_amdgcn_permlane32_swap(__float_as_uint(pmax), __float_as_uint(pmax), false, false);
;     pmax = fmaxf(__uint_as_float(rr[0]), __uint_as_float(rr[1])); }
;   if (__builtin_expect(__all(pmax - m_reg <= THR / SCALE), 1)) { mn = m_reg; alpha = 1.f; }
;   else { mn = fmaxf(m_reg, pmax); alpha = __builtin_amdgcn_exp2f((m_reg - mn) * C); m_reg = mn; }
;   const float mnC = -mn * C;
; #pragma unroll
;   for (int r = 0; r < 16; ++r) p0[r] = fmaf(p0[r], C, mnC);
; #pragma unroll
;   for (int r = 0; r < 16; ++r) p1[r] = fmaf(p1[r], C, mnC);
; #pragma unroll
;   for (int r = 0; r < 16; ++r) p0[r] = __builtin_amdgcn_exp2f(p0[r]);
	v_mfma_f32_32x32x16_bf16 v[18:33], v[114:117], v[196:199], v[18:33]
	v_max_f32_e32 v114, v51, v51
	v_max_f32_e32 v115, v50, v50
	v_max_f32_e32 v114, v115, v114
	v_max3_f32 v114, v114, v52, v53
	v_max3_f32 v114, v114, v54, v55
	v_max3_f32 v114, v114, v56, v57
	v_max3_f32 v114, v114, v58, v59
	v_max3_f32 v114, v114, v60, v61
	v_max3_f32 v114, v114, v62, v63
	v_mfma_f32_32x32x16_bf16 v[18:33], v[118:121], v[200:203], v[18:33]
	v_max3_f32 v114, v114, v64, v65
	v_max3_f32 v114, v114, v34, v35
	v_max3_f32 v114, v114, v36, v37
	v_max3_f32 v114, v114, v38, v39
	v_max3_f32 v114, v114, v40, v41
	v_max3_f32 v114, v114, v42, v43
	v_max3_f32 v114, v114, v44, v45
	v_max3_f32 v114, v114, v46, v47
	v_mfma_f32_32x32x16_bf16 v[18:33], v[124:127], v[204:207], v[18:33]
	v_max3_f32 v114, v114, v48, v49
	v_mov_b32_e32 v115, v114
	s_nop 1
	v_permlane32_swap_b32_e32 v114, v115
	v_max_f32_e32 v115, v115, v115
	v_max_f32_e32 v114, v114, v114
	v_max_f32_e32 v114, v114, v115
	v_sub_f32_e32 v115, v114, v122
	v_cmp_ge_f32_e32 vcc, s13, v115
	v_max_f32_e32 v115, v122, v122
	v_max_f32_e32 v114, v115, v114
	v_mfma_f32_32x32x16_bf16 v[18:33], v[192:195], v[208:211], v[18:33]
	v_sub_f32_e32 v115, v122, v114
	v_mul_f32_e32 v115, 0x3e16c740, v115
	v_exp_f32_e32 v115, v115
	s_cmp_eq_u64 vcc, exec
	s_cselect_b64 s[36:37], -1, 0
	s_waitcnt lgkmcnt(0)
	v_cndmask_b32_e64 v192, v115, 1.0, s[36:37]
	v_cmp_gt_f32_e32 vcc, 1.0, v192
	s_barrier
	s_waitcnt vmcnt(3)
	ds_write_b128 v164, v[98:101]
	ds_write_b128 v165, v[90:93] offset:16384
	ds_write_b128 v166, v[94:97] offset:16384
	s_cbranch_vccz .LBB0_2505
	s_and_saveexec_b64 s[8:9], s[0:1]
	ds_write_b32 v162, v192 offset:49280
	s_or_b64 exec, exec, s[8:9]
	s_waitcnt lgkmcnt(0)
	v_add_u32_e32 v115, v131, v132
	ds_read_b128 v[116:119], v115 offset:49376
	ds_read_b128 v[124:127], v115 offset:49344
	ds_read_b128 v[194:197], v115 offset:49312
	ds_read_b128 v[198:201], v115 offset:49280
	s_waitcnt lgkmcnt(0)
	v_pk_mul_f32 v[14:15], v[14:15], v[116:117]
	v_pk_mul_f32 v[10:11], v[10:11], v[124:125]
	v_pk_mul_f32 v[6:7], v[6:7], v[194:195]
	v_pk_mul_f32 v[16:17], v[16:17], v[118:119]
	v_pk_mul_f32 v[12:13], v[12:13], v[126:127]
	v_pk_mul_f32 v[8:9], v[8:9], v[196:197]
	v_pk_mul_f32 v[4:5], v[4:5], v[200:201]
	v_pk_mul_f32 v[2:3], v[2:3], v[198:199]
	v_pk_mul_f32 v[30:31], v[30:31], v[116:117]
	v_pk_mul_f32 v[26:27], v[26:27], v[124:125]
	v_pk_mul_f32 v[22:23], v[22:23], v[194:195]
	v_pk_mul_f32 v[32:33], v[32:33], v[118:119]
	v_pk_mul_f32 v[28:29], v[28:29], v[126:127]
	v_pk_mul_f32 v[24:25], v[24:25], v[196:197]
	v_pk_mul_f32 v[20:21], v[20:21], v[200:201]
	v_pk_mul_f32 v[18:19], v[18:19], v[198:199]
.LBB0_2505:
	v_cndmask_b32_e64 v193, v114, v122, s[36:37]
	v_mul_f32_e32 v194, 0xbe16c740, v193
	v_fmamk_f32 v50, v50, 0x3e16c740, v194
	v_fmamk_f32 v51, v51, 0x3e16c740, v194
	v_fmamk_f32 v52, v52, 0x3e16c740, v194
	v_fmamk_f32 v53, v53, 0x3e16c740, v194
	v_fmamk_f32 v54, v54, 0x3e16c740, v194
	v_fmamk_f32 v55, v55, 0x3e16c740, v194
	v_fmamk_f32 v56, v56, 0x3e16c740, v194
	v_fmamk_f32 v57, v57, 0x3e16c740, v194
	v_fmamk_f32 v58, v58, 0x3e16c740, v194
	v_fmamk_f32 v59, v59, 0x3e16c740, v194
	v_fmamk_f32 v60, v60, 0x3e16c740, v194
	v_fmamk_f32 v61, v61, 0x3e16c740, v194
	v_fmamk_f32 v62, v62, 0x3e16c740, v194
	v_fmamk_f32 v63, v63, 0x3e16c740, v194
	v_fmamk_f32 v64, v64, 0x3e16c740, v194
	v_fmamk_f32 v65, v65, 0x3e16c740, v194
	v_exp_f32_e32 v114, v50
	v_exp_f32_e32 v129, v51
	v_exp_f32_e32 v115, v52
	v_exp_f32_e32 v128, v53
	v_exp_f32_e32 v116, v54
	v_exp_f32_e32 v127, v55
	v_exp_f32_e32 v117, v56
	v_exp_f32_e32 v126, v57
	v_exp_f32_e32 v118, v58
	v_exp_f32_e32 v125, v59
	v_exp_f32_e32 v119, v60
	v_exp_f32_e32 v124, v61
	v_exp_f32_e32 v120, v62
	v_exp_f32_e32 v123, v63
	v_exp_f32_e32 v121, v64
	v_exp_f32_e32 v122, v65
	v_fmamk_f32 v199, v44, 0x3e16c740, v194
	v_fmamk_f32 v200, v45, 0x3e16c740, v194
	v_fmamk_f32 v202, v34, 0x3e16c740, v194
	v_fmamk_f32 v203, v35, 0x3e16c740, v194
	v_fmamk_f32 v204, v36, 0x3e16c740, v194
	v_fmamk_f32 v205, v37, 0x3e16c740, v194
	v_fmamk_f32 v206, v38, 0x3e16c740, v194
	v_fmamk_f32 v207, v39, 0x3e16c740, v194
	v_fmamk_f32 v195, v40, 0x3e16c740, v194
	v_fmamk_f32 v196, v41, 0x3e16c740, v194
	v_fmamk_f32 v197, v42, 0x3e16c740, v194
	v_fmamk_f32 v198, v43, 0x3e16c740, v194
	v_fmamk_f32 v201, v46, 0x3e16c740, v194
	v_fmamk_f32 v208, v47, 0x3e16c740, v194
	v_fmamk_f32 v209, v48, 0x3e16c740, v194
	v_fmac_f32_e32 v194, 0x3e16c740, v49
	s_waitcnt lgkmcnt(0)
	s_barrier
; DI void partialSM(f32x16& p0, f32x16& p1, float& m_reg, float& mn, float& alpha) {
;   constexpr float C = SCALE * 1.4426950408889634f;
;   float pmax = p0[0];
; #pragma unroll
;   for (int r = 1; r < 16; ++r) pmax = fmaxf(pmax, p0[r]);
; #pragma unroll
;   for (int r = 0; r < 16; ++r) pmax = fmaxf(pmax, p1[r]);
;   { auto rr = __builtin_amdgcn_permlane32_swap(__float_as_uint(pmax), __float_as_uint(pmax), false, false);
;     pmax = fmaxf(__uint_as_float(rr[0]), __uint_as_float(rr[1])); }
;   if (__builtin_expect(__all(pmax - m_reg <= THR / SCALE), 1)) { mn = m_reg; alpha = 1.f; }
;   else { mn = fmaxf(m_reg, pmax); alpha = __builtin_amdgcn_exp2f((m_reg - mn) * C); m_reg = mn; }
;   const float mnC = -mn * C;
; #pragma unroll
;   for (int r = 0; r < 16; ++r) p0[r] = fmaf(p0[r], C, mnC);
; #pragma unroll
;   for (int r = 0; r < 16; ++r) p1[r] = fmaf(p1[r], C, mnC);
; #pragma unroll
;   for (int r = 0; r < 16; ++r) p0[r] = __builtin_amdgcn_exp2f(p0[r]);
; }
; DI void finishSM(f32x16& p0, f32x16& p1, float alpha, float& l_reg, bf16x8& pa0, bf16x8& pa1, bf16x8& pa2, bf16x8& pa3) {
; #pragma unroll
;   for (int r = 0; r < 16; ++r) p1[r] = __builtin_amdgcn_exp2f(p1[r]);
;   float ps = 0;
; #pragma unroll
;   for (int r = 0; r < 16; ++r) ps += p0[r];
; #pragma unroll
;   for (int r = 0; r < 16; ++r) ps += p1[r];
;   { auto rr = __builtin_amdgcn_permlane32_swap(__float_as_uint(ps), __float_as_uint(ps), false, false);
;     ps = __uint_as_float(rr[0]) + __uint_as_float(rr[1]); }
;   l_reg = l_reg * alpha + ps;
;     ...
;   PK4(p0, 0, pa0); PK4(p0, 8, pa1); PK4(p1, 0, pa2); PK4(p1, 8, pa3);
;     ...
; }
; DI void qkt(f32x16& p0, f32x16& p1, const char* Ks, const bf16x8* qr, int r32, int hi) {
;   p0 = f32x16{}; p1 = f32x16{};
; #pragma unroll
;   for (int d0 = 0; d0 < 6; ++d0) { const int cb = (d0 * 16 + hi * 8) * 2;
;     bf16x8 b0 = *reinterpret_cast<const bf16x8*>(Ks + KSWZ(r32, cb));
;     bf16x8 b1 = *reinterpret_cast<const bf16x8*>(Ks + KSWZ(32 + r32, cb));
;     p0 = __builtin_amdgcn_mfma_f32_32x32x16_bf16(b0, qr[d0], p0, 0, 0, 0);
;     p1 = __builtin_amdgcn_mfma_f32_32x32x16_bf16(b1, qr[d0], p1, 0, 0, 0); }
; }
; template <int D0> DI void pv_one(f32x16& od, int vb, bf16x8 pa0, bf16x8 pa1, bf16x8 pa2, bf16x8 pa3) {
	ds_read_b128 v[34:37], v167 offset:16384
	ds_read_b128 v[38:41], v167 offset:24576
	ds_read_b128 v[210:213], v169 offset:16384
	ds_read_b128 v[214:217], v169 offset:24576
	v_exp_f32_e32 v152, v202
	v_exp_f32_e32 v202, v204
	s_waitcnt lgkmcnt(0)
	v_mfma_f32_32x32x16_bf16 v[50:65], v[34:37], v[86:89], 0
	v_exp_f32_e32 v204, v206
	v_exp_f32_e32 v206, v199
	v_add_f32_e32 v199, 0, v114
	v_add_f32_e32 v199, v129, v199
	v_add_f32_e32 v199, v115, v199
	v_add_f32_e32 v199, v128, v199
	v_add_f32_e32 v199, v116, v199
	v_mfma_f32_32x32x16_bf16 v[34:49], v[38:41], v[86:89], 0
	v_add_f32_e32 v199, v127, v199
	v_add_f32_e32 v199, v117, v199
	v_add_f32_e32 v199, v126, v199
	v_add_f32_e32 v199, v118, v199
	v_add_f32_e32 v199, v125, v199
	v_add_f32_e32 v199, v119, v199
	v_add_f32_e32 v199, v124, v199
	v_mfma_f32_32x32x16_bf16 v[50:65], v[210:213], v[82:85], v[50:65]
	v_add_f32_e32 v199, v120, v199
	v_exp_f32_e32 v153, v203
	v_add_f32_e32 v199, v123, v199
	v_add_f32_e32 v199, v121, v199
	v_exp_f32_e32 v203, v205
	v_add_f32_e32 v199, v122, v199
	v_add_f32_e32 v199, v152, v199
	v_mfma_f32_32x32x16_bf16 v[34:49], v[214:217], v[82:85], v[34:49]
	ds_read_b128 v[210:213], v168 offset:16384
	ds_read_b128 v[214:217], v168 offset:24576
	v_exp_f32_e32 v205, v207
	v_add_f32_e32 v199, v153, v199
	v_exp_f32_e32 v195, v195
	v_add_f32_e32 v199, v202, v199
	v_exp_f32_e32 v196, v196
	v_add_f32_e32 v199, v203, v199
	s_waitcnt lgkmcnt(0)
	v_mfma_f32_32x32x16_bf16 v[50:65], v[210:213], v[78:81], v[50:65]
	v_exp_f32_e32 v197, v197
	v_add_f32_e32 v199, v204, v199
	v_exp_f32_e32 v198, v198
	v_add_f32_e32 v199, v205, v199
	v_add_f32_e32 v199, v195, v199
	v_exp_f32_e32 v207, v200
	v_add_f32_e32 v199, v196, v199
	v_mfma_f32_32x32x16_bf16 v[34:49], v[214:217], v[78:81], v[34:49]
	ds_read_b128 v[210:213], v170 offset:16384
	ds_read_b128 v[214:217], v170 offset:24576
	v_exp_f32_e32 v201, v201
	v_add_f32_e32 v199, v197, v199
	v_exp_f32_e32 v208, v208
	v_add_f32_e32 v199, v198, v199
	v_exp_f32_e32 v209, v209
	v_add_f32_e32 v199, v206, v199
	s_waitcnt lgkmcnt(0)
	v_mfma_f32_32x32x16_bf16 v[50:65], v[210:213], v[74:77], v[50:65]
	v_exp_f32_e32 v194, v194
	v_add_f32_e32 v199, v207, v199
	v_add_f32_e32 v199, v201, v199
	v_add_f32_e32 v199, v208, v199
	v_add_f32_e32 v199, v209, v199
	v_add_f32_e32 v199, v194, v199
	v_mov_b32_e32 v200, v199
	v_mfma_f32_32x32x16_bf16 v[34:49], v[214:217], v[74:77], v[34:49]
	ds_read_b128 v[210:213], v188 offset:16384
	ds_read_b128 v[214:217], v188 offset:24576
	v_permlane32_swap_b32_e32 v199, v200
	s_waitcnt lgkmcnt(0)
	v_mfma_f32_32x32x16_bf16 v[50:65], v[210:213], v[70:73], v[50:65]
	v_mfma_f32_32x32x16_bf16 v[34:49], v[214:217], v[70:73], v[34:49]
	ds_read_b128 v[210:213], v171 offset:16384
	ds_read_b128 v[214:217], v171 offset:24576
	v_cvt_pk_bf16_f32 v114, v114, v129
	v_cvt_pk_bf16_f32 v115, v115, v128
	v_cvt_pk_bf16_f32 v116, v116, v127
	v_cvt_pk_bf16_f32 v117, v117, v126
	v_cvt_pk_bf16_f32 v118, v118, v125
	v_cvt_pk_bf16_f32 v119, v119, v124
	s_waitcnt lgkmcnt(0)
	v_mfma_f32_32x32x16_bf16 v[50:65], v[210:213], v[66:69], v[50:65]
	v_cvt_pk_bf16_f32 v120, v120, v123
	v_cvt_pk_bf16_f32 v121, v121, v122
	v_cvt_pk_bf16_f32 v122, v152, v153
	v_cvt_pk_bf16_f32 v123, v202, v203
	v_cvt_pk_bf16_f32 v124, v204, v205
	v_cvt_pk_bf16_f32 v125, v195, v196
	v_cvt_pk_bf16_f32 v126, v197, v198
	v_mfma_f32_32x32x16_bf16 v[34:49], v[214:217], v[66:69], v[34:49]
	v_cvt_pk_bf16_f32 v127, v206, v207
	v_cvt_pk_bf16_f32 v128, v201, v208
	v_cvt_pk_bf16_f32 v129, v209, v194
	v_permlane32_swap_b32_e32 v114, v116
	v_permlane32_swap_b32_e32 v115, v117
	v_permlane32_swap_b32_e32 v118, v120
	v_permlane32_swap_b32_e32 v119, v121
	v_permlane32_swap_b32_e32 v122, v124
	v_permlane32_swap_b32_e32 v123, v125
	v_permlane32_swap_b32_e32 v126, v128
	v_permlane32_swap_b32_e32 v127, v129
	s_cmp_ge_u32 s12, s2
	s_cselect_b64 s[8:9], -1, 0
	s_and_b64 vcc, exec, s[8:9]
	s_cbranch_vccnz .LBB0_2507
	v_add_co_u32_e32 v90, vcc, 0x18540000, v158
	s_nop 1
	v_addc_co_u32_e32 v91, vcc, 0, v159, vcc
	v_add_co_u32_e32 v92, vcc, 0x2f660000, v156
	s_nop 1
	v_addc_co_u32_e32 v93, vcc, 0, v157, vcc
	v_add_co_u32_e32 v94, vcc, 0x2f660000, v140
	global_load_dwordx4 v[98:101], v[90:91], off
	s_nop 0
	global_load_dwordx4 v[90:93], v[92:93], off
	v_addc_co_u32_e32 v95, vcc, 0, v141, vcc
	global_load_dwordx4 v[94:97], v[94:95], off
.LBB0_2507:
	ds_read_b64_tr_b16 v[156:157], v163 offset:0
	ds_read_b64_tr_b16 v[158:159], v163 offset:0x400
	ds_read_b64_tr_b16 v[194:195], v163 offset:0x800
	ds_read_b64_tr_b16 v[196:197], v163 offset:0xc00
	ds_read_b64_tr_b16 v[202:203], v163 offset:0x1000
	ds_read_b64_tr_b16 v[204:205], v163 offset:0x1400
	ds_read_b64_tr_b16 v[206:207], v163 offset:0x1800
	ds_read_b64_tr_b16 v[208:209], v163 offset:0x1c00
	s_waitcnt lgkmcnt(0)
	s_nop 0
	v_mfma_f32_32x32x16_bf16 v[2:17], v[114:117], v[156:159], v[2:17]
	ds_read_b64_tr_b16 v[156:157], v163 offset:0x200
	ds_read_b64_tr_b16 v[158:159], v163 offset:0x600
	v_mfma_f32_32x32x16_bf16 v[2:17], v[118:121], v[194:197], v[2:17]
	ds_read_b64_tr_b16 v[194:195], v163 offset:0xa00
	ds_read_b64_tr_b16 v[196:197], v163 offset:0xe00
	v_mfma_f32_32x32x16_bf16 v[2:17], v[122:125], v[202:205], v[2:17]
	ds_read_b64_tr_b16 v[202:203], v163 offset:0x1200
	ds_read_b64_tr_b16 v[204:205], v163 offset:0x1600
	v_mfma_f32_32x32x16_bf16 v[2:17], v[126:129], v[206:209], v[2:17]
	ds_read_b64_tr_b16 v[206:207], v163 offset:0x1a00
	ds_read_b64_tr_b16 v[208:209], v163 offset:0x1e00
	s_waitcnt lgkmcnt(0)
	v_mfma_f32_32x32x16_bf16 v[18:33], v[114:117], v[156:159], v[18:33]
	v_max_f32_e32 v114, v51, v51
	v_max_f32_e32 v115, v50, v50
	v_max_f32_e32 v114, v115, v114
	v_max3_f32 v114, v114, v52, v53
	v_max3_f32 v114, v114, v54, v55
	v_max3_f32 v114, v114, v56, v57
	v_max3_f32 v114, v114, v58, v59
	v_max3_f32 v114, v114, v60, v61
	v_max3_f32 v114, v114, v62, v63
	v_mfma_f32_32x32x16_bf16 v[18:33], v[118:121], v[194:197], v[18:33]
	v_max3_f32 v114, v114, v64, v65
	v_max3_f32 v114, v114, v34, v35
	v_max3_f32 v114, v114, v36, v37
	v_max3_f32 v114, v114, v38, v39
	v_max3_f32 v114, v114, v40, v41
	v_max3_f32 v114, v114, v42, v43
	v_max3_f32 v114, v114, v44, v45
	v_max3_f32 v114, v114, v46, v47
	v_mfma_f32_32x32x16_bf16 v[18:33], v[122:125], v[202:205], v[18:33]
	v_max3_f32 v114, v114, v48, v49
	v_mov_b32_e32 v115, v114
	s_nop 1
	v_permlane32_swap_b32_e32 v114, v115
	v_max_f32_e32 v115, v115, v115
	v_max_f32_e32 v114, v114, v114
	v_max_f32_e32 v114, v114, v115
	v_sub_f32_e32 v115, v114, v193
	v_cmp_ge_f32_e32 vcc, s13, v115
	v_max_f32_e32 v115, v193, v193
	v_max_f32_e32 v114, v115, v114
	v_mfma_f32_32x32x16_bf16 v[18:33], v[126:129], v[206:209], v[18:33]
	v_sub_f32_e32 v115, v193, v114
	v_mul_f32_e32 v115, 0x3e16c740, v115
	v_exp_f32_e32 v115, v115
	s_cmp_eq_u64 vcc, exec
	s_cselect_b64 s[36:37], -1, 0
	s_waitcnt lgkmcnt(0)
	v_cndmask_b32_e64 v123, v115, 1.0, s[36:37]
	v_cmp_gt_f32_e32 vcc, 1.0, v123
	s_barrier
	s_cmp_ge_u32 s12, s2
	s_cbranch_scc1 .Latt_w0
	s_waitcnt vmcnt(3)
	s_branch .Latt_wd

; #define SWRITE(b, i) do { *(bf16x8*)(V_lds + (b) * SHM_V + vst) = sr_[i].v; *(bf16x8*)(K_lds + (b) * SHM_K + kst1) = sr_[i].k1; *(bf16x8*)(K_lds + (b) * SHM_K + kst2) = sr_[i].k2; } while (0)
; #define RESC(a) do { if (__any((a) < 1.f)) { if (hi == 0) al_l[r32] = (a); asm volatile("s_waitcnt lgkmcnt(0)" ::: "memory"); \
;     _Pragma("unroll") for (int d = 0; d < 2; ++d) _Pragma("unroll") for (int r = 0; r < 16; ++r) o[d][r] *= al_l[crow(r, hi)]; } } while (0)
; DI void attn_body(const bf16_t* __restrict__ Qb, const bf16_t* __restrict__ Kh, const bf16_t* __restrict__ Vh, bf16_t* __restrict__ Ob, int seq, char* lds) {
;     ...
;     __syncthreads(); SWRITE(1, SO);
;     RESC(alA); __syncthreads();
.Latt_wd:
	ds_write_b128 v164, v[102:105] offset:8192
	ds_write_b128 v165, v[106:109] offset:32768
	ds_write_b128 v166, v[110:113] offset:32768
	s_cbranch_vccz .LBB0_2511
	s_and_saveexec_b64 s[20:21], s[0:1]
	ds_write_b32 v162, v123 offset:49280
	s_or_b64 exec, exec, s[20:21]
	s_waitcnt lgkmcnt(0)
	v_add_u32_e32 v115, v131, v132
	ds_read_b128 v[102:105], v115 offset:49376
	ds_read_b128 v[106:109], v115 offset:49344
	ds_read_b128 v[110:113], v115 offset:49312
	ds_read_b128 v[116:119], v115 offset:49280
	s_waitcnt lgkmcnt(3)
	v_pk_mul_f32 v[14:15], v[14:15], v[102:103]
	s_waitcnt lgkmcnt(2)
	v_pk_mul_f32 v[10:11], v[10:11], v[106:107]
	s_waitcnt lgkmcnt(1)
	v_pk_mul_f32 v[6:7], v[6:7], v[110:111]
	v_pk_mul_f32 v[16:17], v[16:17], v[104:105]
	v_pk_mul_f32 v[12:13], v[12:13], v[108:109]
	v_pk_mul_f32 v[8:9], v[8:9], v[112:113]
	s_waitcnt lgkmcnt(0)
	v_pk_mul_f32 v[4:5], v[4:5], v[118:119]
	v_pk_mul_f32 v[2:3], v[2:3], v[116:117]
	v_pk_mul_f32 v[30:31], v[30:31], v[102:103]
	v_pk_mul_f32 v[26:27], v[26:27], v[106:107]
	v_pk_mul_f32 v[22:23], v[22:23], v[110:111]
	v_pk_mul_f32 v[32:33], v[32:33], v[104:105]
	v_pk_mul_f32 v[28:29], v[28:29], v[108:109]
	v_pk_mul_f32 v[24:25], v[24:25], v[112:113]
	v_pk_mul_f32 v[20:21], v[20:21], v[118:119]
	v_pk_mul_f32 v[18:19], v[18:19], v[116:117]
